# pipelined attention loop: 4-deep LDS fragment prefetch for QK^T and PV, softmax-finish VALU interleaved into the QK^T MFMA stream, GQA head map spreads kv groups over XCDs
# speedup vs baseline: 1.0059x; 1.0059x over previous
.LBB0_590:
	ds_read_b128 v[196:199], v185 offset:49152
	ds_read_b128 v[250:253], v185 offset:57344
	ds_read_b128 v[168:171], v186 offset:49152
	ds_read_b128 v[172:175], v186 offset:57344
	v_cndmask_b32_e64 v236, 0, 1, s[18:19]
	v_cmp_ne_u32_e64 s[6:7], 1, v236
	s_andn2_b64 vcc, exec, s[18:19]
	s_waitcnt lgkmcnt(3)
	v_mfma_f32_32x32x16_bf16 v[82:97], v[196:199], v[142:145], 0
	ds_read_b128 v[196:199], v187 offset:49152
	v_add_f32_e32 v232, 0, v223
	v_add_f32_e32 v232, v225, v232
	v_add_f32_e32 v232, v226, v232
	v_add_f32_e32 v232, v227, v232
	v_add_f32_e32 v232, v228, v232
	s_waitcnt lgkmcnt(3)
	v_mfma_f32_32x32x16_bf16 v[66:81], v[250:253], v[142:145], 0
	ds_read_b128 v[250:253], v187 offset:57344
	v_add_f32_e32 v232, v229, v232
	v_add_f32_e32 v232, v230, v232
	v_add_f32_e32 v232, v231, v232
	v_add_f32_e32 v232, v216, v232
	v_add_f32_e32 v232, v217, v232
	s_waitcnt lgkmcnt(3)
	v_mfma_f32_32x32x16_bf16 v[82:97], v[168:171], v[138:141], v[82:97]
	ds_read_b128 v[168:171], v188 offset:49152
	v_add_f32_e32 v232, v218, v232
	v_add_f32_e32 v232, v219, v232
	v_exp_f32_e32 v112, v112
	v_add_f32_e32 v232, v220, v232
	v_exp_f32_e32 v113, v113
	s_waitcnt lgkmcnt(3)
	v_mfma_f32_32x32x16_bf16 v[66:81], v[172:175], v[138:141], v[66:81]
	ds_read_b128 v[172:175], v188 offset:57344
	v_add_f32_e32 v232, v221, v232
	v_exp_f32_e32 v110, v110
	v_add_f32_e32 v232, v222, v232
	v_exp_f32_e32 v111, v111
	v_add_f32_e32 v232, v224, v232
	s_waitcnt lgkmcnt(3)
	v_mfma_f32_32x32x16_bf16 v[82:97], v[196:199], v[134:137], v[82:97]
	ds_read_b128 v[196:199], v189 offset:49152
	v_exp_f32_e32 v108, v108
	v_add_f32_e32 v232, v112, v232
	v_exp_f32_e32 v109, v109
	v_add_f32_e32 v232, v113, v232
	v_exp_f32_e32 v106, v106
	s_waitcnt lgkmcnt(3)
	v_mfma_f32_32x32x16_bf16 v[66:81], v[250:253], v[134:137], v[66:81]
	ds_read_b128 v[250:253], v189 offset:57344
	v_add_f32_e32 v232, v110, v232
	v_exp_f32_e32 v107, v107
	v_add_f32_e32 v232, v111, v232
	v_exp_f32_e32 v104, v104
	v_add_f32_e32 v232, v108, v232
	s_waitcnt lgkmcnt(3)
	v_mfma_f32_32x32x16_bf16 v[82:97], v[168:171], v[130:133], v[82:97]
	ds_read_b128 v[168:171], v205 offset:49152
	v_exp_f32_e32 v105, v105
	v_add_f32_e32 v232, v109, v232
	v_exp_f32_e32 v102, v102
	v_add_f32_e32 v232, v106, v232
	v_exp_f32_e32 v103, v103
	s_waitcnt lgkmcnt(3)
	v_mfma_f32_32x32x16_bf16 v[66:81], v[172:175], v[130:133], v[66:81]
	ds_read_b128 v[172:175], v205 offset:57344
	v_add_f32_e32 v232, v107, v232
	v_exp_f32_e32 v100, v100
	v_add_f32_e32 v232, v104, v232
	v_exp_f32_e32 v101, v101
	v_add_f32_e32 v232, v105, v232
	s_waitcnt lgkmcnt(3)
	v_mfma_f32_32x32x16_bf16 v[82:97], v[196:199], v[126:129], v[82:97]
	ds_read_b128 v[196:199], v206 offset:49152
	v_exp_f32_e32 v98, v98
	v_add_f32_e32 v232, v102, v232
	v_exp_f32_e32 v99, v99
	v_add_f32_e32 v232, v103, v232
	v_add_f32_e32 v232, v100, v232
	s_waitcnt lgkmcnt(3)
	v_mfma_f32_32x32x16_bf16 v[66:81], v[250:253], v[126:129], v[66:81]
	ds_read_b128 v[250:253], v206 offset:57344
	v_add_f32_e32 v232, v101, v232
	v_add_f32_e32 v232, v98, v232
	v_add_f32_e32 v232, v99, v232
	v_mov_b32_e32 v233, v232
	v_cvt_pk_bf16_f32 v235, v226, v227
	s_waitcnt lgkmcnt(3)
	v_mfma_f32_32x32x16_bf16 v[82:97], v[168:171], v[122:125], v[82:97]
	ds_read_b128 v[168:171], v207 offset:49152
	v_cvt_pk_bf16_f32 v237, v230, v231
	v_cvt_pk_bf16_f32 v216, v216, v217
	v_cvt_pk_bf16_f32 v217, v218, v219
	v_cvt_pk_bf16_f32 v218, v220, v221
	v_permlane32_swap_b32_e32 v232, v233
	s_waitcnt lgkmcnt(3)
	v_mfma_f32_32x32x16_bf16 v[66:81], v[172:175], v[122:125], v[66:81]
	ds_read_b128 v[172:175], v207 offset:57344
	v_cvt_pk_bf16_f32 v234, v223, v225
	v_cvt_pk_bf16_f32 v236, v228, v229
	v_permlane32_swap_b32_e32 v235, v237
	v_cvt_pk_bf16_f32 v219, v222, v224
	v_permlane32_swap_b32_e32 v216, v218
	s_waitcnt lgkmcnt(3)
	v_mfma_f32_32x32x16_bf16 v[82:97], v[196:199], v[118:121], v[82:97]
	v_cvt_pk_bf16_f32 v220, v112, v113
	v_cvt_pk_bf16_f32 v221, v110, v111
	v_cvt_pk_bf16_f32 v222, v108, v109
	v_cvt_pk_bf16_f32 v223, v106, v107
	v_cvt_pk_bf16_f32 v224, v104, v105
	s_waitcnt lgkmcnt(2)
	v_mfma_f32_32x32x16_bf16 v[66:81], v[250:253], v[118:121], v[66:81]
	v_cvt_pk_bf16_f32 v225, v102, v103
	v_cvt_pk_bf16_f32 v226, v100, v101
	v_cvt_pk_bf16_f32 v227, v98, v99
	v_permlane32_swap_b32_e32 v234, v236
	v_permlane32_swap_b32_e32 v217, v219
	s_waitcnt lgkmcnt(1)
	v_mfma_f32_32x32x16_bf16 v[82:97], v[168:171], v[114:117], v[82:97]
	v_permlane32_swap_b32_e32 v220, v222
	v_permlane32_swap_b32_e32 v221, v223
	v_permlane32_swap_b32_e32 v224, v226
	v_permlane32_swap_b32_e32 v225, v227
	s_waitcnt lgkmcnt(0)
	v_mfma_f32_32x32x16_bf16 v[66:81], v[172:175], v[114:117], v[66:81]
	s_cbranch_vccnz .LBB0_592
	v_add_u32_e32 v255, 27, v215
	v_cmp_lt_i32_e32 vcc, s84, v255
	v_cmp_gt_i32_e64 s[8:9], s88, v255
	s_or_b64 vcc, vcc, s[8:9]
	v_add_u32_e32 v255, -5, v215
	s_nop 2
	v_cndmask_b32_e32 v82, v82, v203, vcc
	v_cmp_lt_i32_e32 vcc, s84, v255
	v_cmp_gt_i32_e64 s[8:9], s88, v255
	s_or_b64 vcc, vcc, s[8:9]
	v_add_u32_e32 v255, 26, v215
	v_cndmask_b32_e32 v66, v66, v203, vcc
	v_cmp_lt_i32_e32 vcc, s84, v255
	v_cmp_gt_i32_e64 s[8:9], s88, v255
	s_or_b64 vcc, vcc, s[8:9]
	v_add_u32_e32 v255, -6, v215
	v_cndmask_b32_e32 v83, v83, v203, vcc
	v_cmp_lt_i32_e32 vcc, s84, v255
	v_cmp_gt_i32_e64 s[8:9], s88, v255
	s_or_b64 vcc, vcc, s[8:9]
	v_add_u32_e32 v255, 25, v215
	v_cndmask_b32_e32 v67, v67, v203, vcc
	v_cmp_lt_i32_e32 vcc, s84, v255
	v_cmp_gt_i32_e64 s[8:9], s88, v255
	s_or_b64 vcc, vcc, s[8:9]
	v_add_u32_e32 v255, -7, v215
	v_cndmask_b32_e32 v84, v84, v203, vcc
	v_cmp_lt_i32_e32 vcc, s84, v255
	v_cmp_gt_i32_e64 s[8:9], s88, v255
	s_or_b64 vcc, vcc, s[8:9]
	v_add_u32_e32 v255, 24, v215
	v_cndmask_b32_e32 v68, v68, v203, vcc
	v_cmp_lt_i32_e32 vcc, s84, v255
	v_cmp_gt_i32_e64 s[8:9], s88, v255
	s_or_b64 vcc, vcc, s[8:9]
	v_add_u32_e32 v255, -8, v215
	v_cndmask_b32_e32 v85, v85, v203, vcc
	v_cmp_lt_i32_e32 vcc, s84, v255
	v_cmp_gt_i32_e64 s[8:9], s88, v255
	s_or_b64 vcc, vcc, s[8:9]
	v_add_u32_e32 v255, 19, v215
	v_cndmask_b32_e32 v69, v69, v203, vcc
	v_cmp_lt_i32_e32 vcc, s84, v255
	v_cmp_gt_i32_e64 s[8:9], s88, v255
	s_or_b64 vcc, vcc, s[8:9]
	v_add_u32_e32 v255, -13, v215
	v_cndmask_b32_e32 v86, v86, v203, vcc
	v_cmp_lt_i32_e32 vcc, s84, v255
	v_cmp_gt_i32_e64 s[8:9], s88, v255
	s_or_b64 vcc, vcc, s[8:9]
	v_add_u32_e32 v255, 18, v215
	v_cndmask_b32_e32 v70, v70, v203, vcc
	v_cmp_lt_i32_e32 vcc, s84, v255
	v_cmp_gt_i32_e64 s[8:9], s88, v255
	s_or_b64 vcc, vcc, s[8:9]
	v_add_u32_e32 v255, -14, v215
	v_cndmask_b32_e32 v87, v87, v203, vcc
	v_cmp_lt_i32_e32 vcc, s84, v255
	v_cmp_gt_i32_e64 s[8:9], s88, v255
	s_or_b64 vcc, vcc, s[8:9]
	v_add_u32_e32 v255, 17, v215
	v_cndmask_b32_e32 v71, v71, v203, vcc
	v_cmp_lt_i32_e32 vcc, s84, v255
	v_cmp_gt_i32_e64 s[8:9], s88, v255
	s_or_b64 vcc, vcc, s[8:9]
	v_add_u32_e32 v255, -15, v215
	v_cndmask_b32_e32 v88, v88, v203, vcc
	v_cmp_lt_i32_e32 vcc, s84, v255
	v_cmp_gt_i32_e64 s[8:9], s88, v255
	s_or_b64 vcc, vcc, s[8:9]
	v_add_u32_e32 v255, 16, v215
	v_cndmask_b32_e32 v72, v72, v203, vcc
	v_cmp_lt_i32_e32 vcc, s84, v255
	v_cmp_gt_i32_e64 s[8:9], s88, v255
	s_or_b64 vcc, vcc, s[8:9]
	v_add_u32_e32 v255, -16, v215
	v_cndmask_b32_e32 v89, v89, v203, vcc
	v_cmp_lt_i32_e32 vcc, s84, v255
	v_cmp_gt_i32_e64 s[8:9], s88, v255
	s_or_b64 vcc, vcc, s[8:9]
	v_add_u32_e32 v255, 11, v215
	v_cndmask_b32_e32 v73, v73, v203, vcc
	v_cmp_lt_i32_e32 vcc, s84, v255
	v_cmp_gt_i32_e64 s[8:9], s88, v255
	s_or_b64 vcc, vcc, s[8:9]
	v_subrev_u32_e32 v255, 21, v215
	v_cndmask_b32_e32 v90, v90, v203, vcc
	v_cmp_lt_i32_e32 vcc, s84, v255
	v_cmp_gt_i32_e64 s[8:9], s88, v255
	s_or_b64 vcc, vcc, s[8:9]
	v_add_u32_e32 v255, 10, v215
	v_cndmask_b32_e32 v74, v74, v203, vcc
	v_cmp_lt_i32_e32 vcc, s84, v255
	v_cmp_gt_i32_e64 s[8:9], s88, v255
	s_or_b64 vcc, vcc, s[8:9]
	v_subrev_u32_e32 v255, 22, v215
	v_cndmask_b32_e32 v91, v91, v203, vcc
	v_cmp_lt_i32_e32 vcc, s84, v255
	v_cmp_gt_i32_e64 s[8:9], s88, v255
	s_or_b64 vcc, vcc, s[8:9]
	v_add_u32_e32 v255, 9, v215
	v_cndmask_b32_e32 v75, v75, v203, vcc
	v_cmp_lt_i32_e32 vcc, s84, v255
	v_cmp_gt_i32_e64 s[8:9], s88, v255
	s_or_b64 vcc, vcc, s[8:9]
	v_subrev_u32_e32 v255, 23, v215
	v_cndmask_b32_e32 v92, v92, v203, vcc
	v_cmp_lt_i32_e32 vcc, s84, v255
	v_cmp_gt_i32_e64 s[8:9], s88, v255
	s_or_b64 vcc, vcc, s[8:9]
	v_add_u32_e32 v255, 8, v215
	v_cndmask_b32_e32 v76, v76, v203, vcc
	v_cmp_lt_i32_e32 vcc, s84, v255
	v_cmp_gt_i32_e64 s[8:9], s88, v255
	s_or_b64 vcc, vcc, s[8:9]
	v_subrev_u32_e32 v255, 24, v215
	v_cndmask_b32_e32 v93, v93, v203, vcc
	v_cmp_lt_i32_e32 vcc, s84, v255
	v_cmp_gt_i32_e64 s[8:9], s88, v255
	s_or_b64 vcc, vcc, s[8:9]
	v_add_u32_e32 v255, 3, v215
	v_cndmask_b32_e32 v77, v77, v203, vcc
	v_cmp_lt_i32_e32 vcc, s84, v255
	v_cmp_gt_i32_e64 s[8:9], s88, v255
	s_or_b64 vcc, vcc, s[8:9]
	v_subrev_u32_e32 v255, 29, v215
	v_cndmask_b32_e32 v94, v94, v203, vcc
	v_cmp_lt_i32_e32 vcc, s84, v255
	v_cmp_gt_i32_e64 s[8:9], s88, v255
	s_or_b64 vcc, vcc, s[8:9]
	v_add_u32_e32 v255, 2, v215
	v_cndmask_b32_e32 v78, v78, v203, vcc
	v_cmp_lt_i32_e32 vcc, s84, v255
	v_cmp_gt_i32_e64 s[8:9], s88, v255
	s_or_b64 vcc, vcc, s[8:9]
	v_subrev_u32_e32 v255, 30, v215
	v_cndmask_b32_e32 v95, v95, v203, vcc
	v_cmp_lt_i32_e32 vcc, s84, v255
	v_cmp_gt_i32_e64 s[8:9], s88, v255
	s_or_b64 vcc, vcc, s[8:9]
	v_add_u32_e32 v255, 1, v215
	v_cndmask_b32_e32 v79, v79, v203, vcc
	v_cmp_lt_i32_e32 vcc, s84, v255
	v_cmp_gt_i32_e64 s[8:9], s88, v255
	s_or_b64 vcc, vcc, s[8:9]
	v_subrev_u32_e32 v255, 31, v215
	v_cndmask_b32_e32 v96, v96, v203, vcc
	v_cmp_lt_i32_e32 vcc, s84, v255
	v_cmp_gt_i32_e64 s[8:9], s88, v255
	s_or_b64 vcc, vcc, s[8:9]
	v_cndmask_b32_e32 v80, v80, v203, vcc
	v_cmp_lt_i32_e32 vcc, s84, v215
	v_cmp_gt_i32_e64 s[8:9], s88, v215
	s_or_b64 vcc, vcc, s[8:9]
	v_subrev_u32_e32 v255, 32, v215
	v_cndmask_b32_e32 v97, v97, v203, vcc
	v_cmp_lt_i32_e32 vcc, s84, v255
	v_cmp_gt_i32_e64 s[8:9], s88, v255
	s_or_b64 vcc, vcc, s[8:9]
	v_cndmask_b32_e32 v81, v81, v203, vcc
.LBB0_592:
	v_lshl_add_u64 v[98:99], v[156:157], 0, s[22:23]
	v_lshl_add_u64 v[102:103], v[158:159], 0, s[22:23]
	v_lshl_add_u64 v[106:107], v[160:161], 0, s[22:23]
	v_lshl_add_u64 v[110:111], v[162:163], 0, s[22:23]
	global_load_dwordx4 v[98:101], v[98:99], off
	s_nop 0
	global_load_dwordx4 v[102:105], v[102:103], off
	s_nop 0
	global_load_dwordx4 v[106:109], v[106:107], off
	s_nop 0
	global_load_dwordx4 v[110:113], v[110:111], off
	ds_read_b64_tr_b16 v[228:229], v184 offset:0
	ds_read_b64_tr_b16 v[230:231], v184 offset:2048
	ds_read_b64_tr_b16 v[242:243], v184 offset:4096
	ds_read_b64_tr_b16 v[244:245], v184 offset:6144
	ds_read_b64_tr_b16 v[196:197], v184 offset:8192
	ds_read_b64_tr_b16 v[198:199], v184 offset:10240
	s_waitcnt lgkmcnt(4)
	v_mfma_f32_32x32x16_bf16 v[50:65], v[234:237], v[228:231], v[50:65]
	ds_read_b64_tr_b16 v[238:239], v184 offset:12288
	ds_read_b64_tr_b16 v[240:241], v184 offset:14336
	s_waitcnt lgkmcnt(4)
	v_mfma_f32_32x32x16_bf16 v[50:65], v[216:219], v[242:245], v[50:65]
	ds_read_b64_tr_b16 v[228:229], v184 offset:512
	ds_read_b64_tr_b16 v[230:231], v184 offset:2560
	s_waitcnt lgkmcnt(4)
	v_mfma_f32_32x32x16_bf16 v[50:65], v[220:223], v[196:199], v[50:65]
	ds_read_b64_tr_b16 v[242:243], v184 offset:4608
	ds_read_b64_tr_b16 v[244:245], v184 offset:6656
	s_waitcnt lgkmcnt(4)
	v_mfma_f32_32x32x16_bf16 v[50:65], v[224:227], v[238:241], v[50:65]
	ds_read_b64_tr_b16 v[196:197], v184 offset:8704
	ds_read_b64_tr_b16 v[198:199], v184 offset:10752
	s_waitcnt lgkmcnt(4)
	v_mfma_f32_32x32x16_bf16 v[34:49], v[234:237], v[228:231], v[34:49]
	ds_read_b64_tr_b16 v[238:239], v184 offset:12800
	ds_read_b64_tr_b16 v[240:241], v184 offset:14848
	s_waitcnt lgkmcnt(4)
	v_mfma_f32_32x32x16_bf16 v[34:49], v[216:219], v[242:245], v[34:49]
	ds_read_b64_tr_b16 v[228:229], v184 offset:1024
	ds_read_b64_tr_b16 v[230:231], v184 offset:3072
	s_waitcnt lgkmcnt(4)
	v_mfma_f32_32x32x16_bf16 v[34:49], v[220:223], v[196:199], v[34:49]
	ds_read_b64_tr_b16 v[242:243], v184 offset:5120
	ds_read_b64_tr_b16 v[244:245], v184 offset:7168
	s_waitcnt lgkmcnt(4)
	v_mfma_f32_32x32x16_bf16 v[34:49], v[224:227], v[238:241], v[34:49]
	ds_read_b64_tr_b16 v[196:197], v184 offset:9216
	ds_read_b64_tr_b16 v[198:199], v184 offset:11264
	s_waitcnt lgkmcnt(4)
	v_mfma_f32_32x32x16_bf16 v[18:33], v[234:237], v[228:231], v[18:33]
	ds_read_b64_tr_b16 v[238:239], v184 offset:13312
	ds_read_b64_tr_b16 v[240:241], v184 offset:15360
	s_waitcnt lgkmcnt(4)
	v_mfma_f32_32x32x16_bf16 v[18:33], v[216:219], v[242:245], v[18:33]
	ds_read_b64_tr_b16 v[228:229], v184 offset:1536
	ds_read_b64_tr_b16 v[230:231], v184 offset:3584
	s_waitcnt lgkmcnt(4)
	v_mfma_f32_32x32x16_bf16 v[18:33], v[220:223], v[196:199], v[18:33]
	ds_read_b64_tr_b16 v[242:243], v184 offset:5632
	ds_read_b64_tr_b16 v[244:245], v184 offset:7680
	s_waitcnt lgkmcnt(4)
	v_mfma_f32_32x32x16_bf16 v[18:33], v[224:227], v[238:241], v[18:33]
	ds_read_b64_tr_b16 v[196:197], v184 offset:9728
	ds_read_b64_tr_b16 v[198:199], v184 offset:11776
	s_waitcnt lgkmcnt(4)
	v_mfma_f32_32x32x16_bf16 v[2:17], v[234:237], v[228:231], v[2:17]
	ds_read_b64_tr_b16 v[238:239], v184 offset:13824
	ds_read_b64_tr_b16 v[240:241], v184 offset:15872
	s_waitcnt lgkmcnt(4)
	v_mfma_f32_32x32x16_bf16 v[2:17], v[216:219], v[242:245], v[2:17]
	v_max_f32_e32 v216, v83, v83
	v_max_f32_e32 v217, v82, v82
	v_max_f32_e32 v216, v217, v216
	v_max3_f32 v216, v216, v84, v85
	v_max3_f32 v216, v216, v86, v87
	v_max3_f32 v216, v216, v88, v89
	v_max3_f32 v216, v216, v90, v91
	v_max3_f32 v216, v216, v92, v93
	v_max3_f32 v216, v216, v94, v95
	v_max3_f32 v216, v216, v96, v97
	v_max3_f32 v216, v216, v66, v67
	v_max3_f32 v216, v216, v68, v69
	v_max3_f32 v216, v216, v70, v71
	v_max3_f32 v216, v216, v72, v73
	v_max3_f32 v216, v216, v74, v75
	v_max3_f32 v216, v216, v76, v77
	v_max3_f32 v216, v216, v78, v79
	s_waitcnt lgkmcnt(2)
	v_mfma_f32_32x32x16_bf16 v[2:17], v[220:223], v[196:199], v[2:17]
	v_max3_f32 v216, v216, v80, v81
	v_mov_b32_e32 v217, v216
	s_nop 1
	v_permlane32_swap_b32_e32 v216, v217
	v_max_f32_e32 v217, v217, v217
	v_max_f32_e32 v216, v216, v216
	v_max_f32_e32 v216, v216, v217
	v_sub_f32_e32 v217, v216, v212
	v_cmp_ge_f32_e32 vcc, s40, v217
	v_max_f32_e32 v217, v212, v212
	v_max_f32_e32 v216, v217, v216
	s_waitcnt lgkmcnt(0)
	v_mfma_f32_32x32x16_bf16 v[2:17], v[224:227], v[238:241], v[2:17]
	v_sub_f32_e32 v217, v212, v216
	v_mul_f32_e32 v217, 0x3e0293ee, v217
	s_barrier
	s_waitcnt vmcnt(3)
	ds_write_b128 v208, v[98:101]
	s_waitcnt vmcnt(2)
	ds_write_b128 v209, v[102:105]
	s_waitcnt vmcnt(1)
	ds_write_b128 v210, v[106:109] offset:32768
	s_waitcnt vmcnt(0)
	ds_write_b128 v211, v[110:113] offset:32768
	v_exp_f32_e32 v98, v217
	s_cmp_eq_u64 vcc, exec
	s_cselect_b64 s[8:9], -1, 0
	v_cndmask_b32_e64 v235, v98, 1.0, s[8:9]
	v_cmp_gt_f32_e32 vcc, 1.0, v235
	s_cbranch_vccz .LBB0_596
	s_and_saveexec_b64 s[60:61], s[4:5]
	ds_write_b32 v183, v235 offset:128
	s_or_b64 exec, exec, s[60:61]
	s_waitcnt lgkmcnt(0)
	v_add_u32_e32 v110, v181, v146
	ds_read_b128 v[98:101], v110 offset:224
	ds_read_b128 v[102:105], v110 offset:192
	ds_read_b128 v[106:109], v110 offset:160
	ds_read_b128 v[110:113], v110 offset:128
	s_waitcnt lgkmcnt(3)
	v_pk_mul_f32 v[62:63], v[62:63], v[98:99]
	s_waitcnt lgkmcnt(2)
	v_pk_mul_f32 v[58:59], v[58:59], v[102:103]
	s_waitcnt lgkmcnt(1)
	v_pk_mul_f32 v[54:55], v[54:55], v[106:107]
	v_pk_mul_f32 v[64:65], v[64:65], v[100:101]
	v_pk_mul_f32 v[60:61], v[60:61], v[104:105]
	v_pk_mul_f32 v[56:57], v[56:57], v[108:109]
	s_waitcnt lgkmcnt(0)
	v_pk_mul_f32 v[52:53], v[52:53], v[112:113]
	v_pk_mul_f32 v[50:51], v[50:51], v[110:111]
	v_pk_mul_f32 v[46:47], v[46:47], v[98:99]
	v_pk_mul_f32 v[42:43], v[42:43], v[102:103]
	v_pk_mul_f32 v[38:39], v[38:39], v[106:107]
	v_pk_mul_f32 v[48:49], v[48:49], v[100:101]
	v_pk_mul_f32 v[44:45], v[44:45], v[104:105]
	v_pk_mul_f32 v[40:41], v[40:41], v[108:109]
	v_pk_mul_f32 v[36:37], v[36:37], v[112:113]
	v_pk_mul_f32 v[34:35], v[34:35], v[110:111]
	v_pk_mul_f32 v[30:31], v[30:31], v[98:99]
	v_pk_mul_f32 v[26:27], v[26:27], v[102:103]
	v_pk_mul_f32 v[22:23], v[22:23], v[106:107]
	v_pk_mul_f32 v[32:33], v[32:33], v[100:101]
	v_pk_mul_f32 v[28:29], v[28:29], v[104:105]
	v_pk_mul_f32 v[24:25], v[24:25], v[108:109]
	v_pk_mul_f32 v[20:21], v[20:21], v[112:113]
	v_pk_mul_f32 v[18:19], v[18:19], v[110:111]
	v_pk_mul_f32 v[14:15], v[14:15], v[98:99]
	v_pk_mul_f32 v[10:11], v[10:11], v[102:103]
	v_pk_mul_f32 v[6:7], v[6:7], v[106:107]
	v_pk_mul_f32 v[16:17], v[16:17], v[100:101]
	v_pk_mul_f32 v[12:13], v[12:13], v[104:105]
	v_pk_mul_f32 v[8:9], v[8:9], v[108:109]
	v_pk_mul_f32 v[4:5], v[4:5], v[112:113]
	v_pk_mul_f32 v[2:3], v[2:3], v[110:111]
.LBB0_596:
	v_cndmask_b32_e64 v212, v216, v212, s[8:9]
	v_mul_f32_e32 v227, 0xbe0293ee, v212
	v_fmamk_f32 v82, v82, 0x3e0293ee, v227
	v_fmamk_f32 v83, v83, 0x3e0293ee, v227
	v_fmamk_f32 v84, v84, 0x3e0293ee, v227
	v_fmamk_f32 v85, v85, 0x3e0293ee, v227
	v_fmamk_f32 v86, v86, 0x3e0293ee, v227
	v_fmamk_f32 v87, v87, 0x3e0293ee, v227
	v_fmamk_f32 v88, v88, 0x3e0293ee, v227
	v_fmamk_f32 v89, v89, 0x3e0293ee, v227
	v_fmamk_f32 v90, v90, 0x3e0293ee, v227
	v_fmamk_f32 v91, v91, 0x3e0293ee, v227
	v_fmamk_f32 v92, v92, 0x3e0293ee, v227
	v_fmamk_f32 v93, v93, 0x3e0293ee, v227
	v_fmamk_f32 v94, v94, 0x3e0293ee, v227
	v_fmamk_f32 v95, v95, 0x3e0293ee, v227
	v_fmamk_f32 v96, v96, 0x3e0293ee, v227
	v_fmamk_f32 v97, v97, 0x3e0293ee, v227
	v_fmamk_f32 v234, v66, 0x3e0293ee, v227
	v_fmamk_f32 v231, v68, 0x3e0293ee, v227
	v_fmamk_f32 v230, v70, 0x3e0293ee, v227
	v_fmamk_f32 v229, v72, 0x3e0293ee, v227
	v_fmamk_f32 v228, v74, 0x3e0293ee, v227
	v_exp_f32_e32 v72, v82
	v_exp_f32_e32 v217, v83
	v_exp_f32_e32 v218, v84
	v_exp_f32_e32 v221, v85
	v_exp_f32_e32 v222, v86
	v_exp_f32_e32 v224, v87
	v_exp_f32_e32 v225, v88
	v_exp_f32_e32 v226, v89
	v_exp_f32_e32 v66, v90
	v_exp_f32_e32 v68, v91
	v_exp_f32_e32 v70, v92
	v_exp_f32_e32 v74, v93
	v_exp_f32_e32 v216, v94
	v_exp_f32_e32 v219, v95
	v_exp_f32_e32 v220, v96
	v_exp_f32_e32 v223, v97
	v_fmamk_f32 v236, v76, 0x3e0293ee, v227
	v_fmamk_f32 v78, v78, 0x3e0293ee, v227
	v_fmamk_f32 v76, v80, 0x3e0293ee, v227
	s_waitcnt lgkmcnt(0)
	s_barrier
	ds_read_b128 v[196:199], v185 offset:32768
	ds_read_b128 v[250:253], v185 offset:40960
	ds_read_b128 v[168:171], v186 offset:32768
	ds_read_b128 v[172:175], v186 offset:40960
	s_and_b64 vcc, exec, s[6:7]
	s_waitcnt lgkmcnt(3)
	v_mfma_f32_32x32x16_bf16 v[98:113], v[196:199], v[142:145], 0
	ds_read_b128 v[196:199], v187 offset:32768
	v_fmamk_f32 v67, v67, 0x3e0293ee, v227
	v_fmamk_f32 v69, v69, 0x3e0293ee, v227
	v_fmamk_f32 v71, v71, 0x3e0293ee, v227
	v_fmamk_f32 v73, v73, 0x3e0293ee, v227
	v_fmamk_f32 v75, v75, 0x3e0293ee, v227
	v_fmamk_f32 v77, v77, 0x3e0293ee, v227
	s_waitcnt lgkmcnt(3)
	v_mfma_f32_32x32x16_bf16 v[82:97], v[250:253], v[142:145], 0
	ds_read_b128 v[250:253], v187 offset:40960
	v_fmamk_f32 v79, v79, 0x3e0293ee, v227
	v_fmac_f32_e32 v227, 0x3e0293ee, v81
	v_exp_f32_e32 v245, v227
	v_add_f32_e32 v227, 0, v72
	v_add_f32_e32 v227, v217, v227
	v_add_f32_e32 v227, v218, v227
	s_waitcnt lgkmcnt(3)
	v_mfma_f32_32x32x16_bf16 v[98:113], v[168:171], v[138:141], v[98:113]
	ds_read_b128 v[168:171], v188 offset:32768
	v_add_f32_e32 v227, v221, v227
	v_add_f32_e32 v227, v222, v227
	v_add_f32_e32 v227, v224, v227
	v_add_f32_e32 v227, v225, v227
	v_add_f32_e32 v227, v226, v227
	v_add_f32_e32 v227, v66, v227
	s_waitcnt lgkmcnt(3)
	v_mfma_f32_32x32x16_bf16 v[82:97], v[172:175], v[138:141], v[82:97]
	ds_read_b128 v[172:175], v188 offset:40960
	v_add_f32_e32 v227, v68, v227
	v_add_f32_e32 v227, v70, v227
	v_add_f32_e32 v227, v74, v227
	v_exp_f32_e32 v80, v234
	v_add_f32_e32 v227, v216, v227
	v_exp_f32_e32 v67, v67
	s_waitcnt lgkmcnt(3)
	v_mfma_f32_32x32x16_bf16 v[98:113], v[196:199], v[134:137], v[98:113]
	ds_read_b128 v[196:199], v189 offset:32768
	v_add_f32_e32 v227, v219, v227
	v_exp_f32_e32 v81, v231
	v_add_f32_e32 v227, v220, v227
	v_exp_f32_e32 v69, v69
	v_add_f32_e32 v227, v223, v227
	v_exp_f32_e32 v234, v230
	s_waitcnt lgkmcnt(3)
	v_mfma_f32_32x32x16_bf16 v[82:97], v[250:253], v[134:137], v[82:97]
	ds_read_b128 v[250:253], v189 offset:40960
	v_add_f32_e32 v227, v80, v227
	v_exp_f32_e32 v71, v71
	v_add_f32_e32 v227, v67, v227
	v_exp_f32_e32 v242, v229
	v_add_f32_e32 v227, v81, v227
	v_exp_f32_e32 v73, v73
	s_waitcnt lgkmcnt(3)
	v_mfma_f32_32x32x16_bf16 v[98:113], v[168:171], v[130:133], v[98:113]
	ds_read_b128 v[168:171], v205 offset:32768
	v_add_f32_e32 v227, v69, v227
	v_exp_f32_e32 v243, v228
	v_add_f32_e32 v227, v234, v227
	v_exp_f32_e32 v75, v75
	v_add_f32_e32 v227, v71, v227
	v_exp_f32_e32 v244, v236
	s_waitcnt lgkmcnt(3)
	v_mfma_f32_32x32x16_bf16 v[82:97], v[172:175], v[130:133], v[82:97]
	ds_read_b128 v[172:175], v205 offset:40960
	v_add_f32_e32 v227, v242, v227
	v_exp_f32_e32 v77, v77
	v_add_f32_e32 v227, v73, v227
	v_exp_f32_e32 v78, v78
	v_add_f32_e32 v227, v243, v227
	v_exp_f32_e32 v79, v79
	s_waitcnt lgkmcnt(3)
	v_mfma_f32_32x32x16_bf16 v[98:113], v[196:199], v[126:129], v[98:113]
	ds_read_b128 v[196:199], v206 offset:32768
	v_add_f32_e32 v227, v75, v227
	v_exp_f32_e32 v76, v76
	v_add_f32_e32 v227, v244, v227
	v_add_f32_e32 v227, v77, v227
	v_add_f32_e32 v227, v78, v227
	v_add_f32_e32 v227, v79, v227
	s_waitcnt lgkmcnt(3)
	v_mfma_f32_32x32x16_bf16 v[82:97], v[250:253], v[126:129], v[82:97]
	ds_read_b128 v[250:253], v206 offset:40960
	v_add_f32_e32 v227, v76, v227
	v_add_f32_e32 v236, v245, v227
	v_mov_b32_e32 v237, v236
	v_cvt_pk_bf16_f32 v229, v218, v221
	v_cvt_pk_bf16_f32 v231, v225, v226
	v_cvt_pk_bf16_f32 v226, v216, v219
	s_waitcnt lgkmcnt(3)
	v_mfma_f32_32x32x16_bf16 v[98:113], v[168:171], v[122:125], v[98:113]
	ds_read_b128 v[168:171], v207 offset:32768
	v_cvt_pk_bf16_f32 v216, v80, v67
	v_cvt_pk_bf16_f32 v218, v234, v71
	v_permlane32_swap_b32_e32 v236, v237
	v_cvt_pk_bf16_f32 v228, v72, v217
	v_cvt_pk_bf16_f32 v230, v222, v224
	v_cvt_pk_bf16_f32 v224, v66, v68
	s_waitcnt lgkmcnt(3)
	v_mfma_f32_32x32x16_bf16 v[82:97], v[172:175], v[122:125], v[82:97]
	ds_read_b128 v[172:175], v207 offset:40960
	v_cvt_pk_bf16_f32 v225, v70, v74
	v_cvt_pk_bf16_f32 v227, v220, v223
	v_cvt_pk_bf16_f32 v217, v81, v69
	v_cvt_pk_bf16_f32 v219, v242, v73
	v_permlane32_swap_b32_e32 v216, v218
	v_cvt_pk_bf16_f32 v220, v243, v75
	s_waitcnt lgkmcnt(3)
	v_mfma_f32_32x32x16_bf16 v[98:113], v[196:199], v[118:121], v[98:113]
	v_cvt_pk_bf16_f32 v221, v244, v77
	v_cvt_pk_bf16_f32 v222, v78, v79
	v_cvt_pk_bf16_f32 v223, v76, v245
	v_permlane32_swap_b32_e32 v228, v230
	v_permlane32_swap_b32_e32 v229, v231
	v_permlane32_swap_b32_e32 v224, v226
	s_waitcnt lgkmcnt(2)
	v_mfma_f32_32x32x16_bf16 v[82:97], v[250:253], v[118:121], v[82:97]
	v_permlane32_swap_b32_e32 v225, v227
	v_permlane32_swap_b32_e32 v217, v219
	v_permlane32_swap_b32_e32 v220, v222
	v_permlane32_swap_b32_e32 v221, v223
	s_waitcnt lgkmcnt(1)
	v_mfma_f32_32x32x16_bf16 v[98:113], v[168:171], v[114:117], v[98:113]
	s_waitcnt lgkmcnt(0)
	v_mfma_f32_32x32x16_bf16 v[82:97], v[172:175], v[114:117], v[82:97]
	s_cbranch_vccnz .LBB0_598
	v_subrev_u32_e32 v80, 37, v215
	v_cmp_lt_i32_e32 vcc, s84, v80
	v_cmp_gt_i32_e64 s[6:7], s88, v80
	s_or_b64 vcc, vcc, s[6:7]
	v_add_u32_e32 v80, 0xffffffbb, v215
	s_nop 2
	v_cndmask_b32_e32 v98, v98, v203, vcc
	v_cmp_lt_i32_e32 vcc, s84, v80
	v_cmp_gt_i32_e64 s[6:7], s88, v80
	s_or_b64 vcc, vcc, s[6:7]
	v_subrev_u32_e32 v80, 38, v215
	v_cndmask_b32_e32 v82, v82, v203, vcc
	v_cmp_lt_i32_e32 vcc, s84, v80
	v_cmp_gt_i32_e64 s[6:7], s88, v80
	s_or_b64 vcc, vcc, s[6:7]
	v_add_u32_e32 v80, 0xffffffba, v215
	v_cndmask_b32_e32 v99, v99, v203, vcc
	v_cmp_lt_i32_e32 vcc, s84, v80
	v_cmp_gt_i32_e64 s[6:7], s88, v80
	s_or_b64 vcc, vcc, s[6:7]
	v_subrev_u32_e32 v80, 39, v215
	v_cndmask_b32_e32 v83, v83, v203, vcc
	v_cmp_lt_i32_e32 vcc, s84, v80
	v_cmp_gt_i32_e64 s[6:7], s88, v80
	s_or_b64 vcc, vcc, s[6:7]
	v_add_u32_e32 v80, 0xffffffb9, v215
	v_cndmask_b32_e32 v100, v100, v203, vcc
	v_cmp_lt_i32_e32 vcc, s84, v80
	v_cmp_gt_i32_e64 s[6:7], s88, v80
	s_or_b64 vcc, vcc, s[6:7]
	v_subrev_u32_e32 v80, 40, v215
	v_cndmask_b32_e32 v84, v84, v203, vcc
	v_cmp_lt_i32_e32 vcc, s84, v80
	v_cmp_gt_i32_e64 s[6:7], s88, v80
	s_or_b64 vcc, vcc, s[6:7]
	v_add_u32_e32 v80, 0xffffffb8, v215
	v_cndmask_b32_e32 v101, v101, v203, vcc
	v_cmp_lt_i32_e32 vcc, s84, v80
	v_cmp_gt_i32_e64 s[6:7], s88, v80
	s_or_b64 vcc, vcc, s[6:7]
	v_subrev_u32_e32 v80, 45, v215
	v_cndmask_b32_e32 v85, v85, v203, vcc
	v_cmp_lt_i32_e32 vcc, s84, v80
	v_cmp_gt_i32_e64 s[6:7], s88, v80
	s_or_b64 vcc, vcc, s[6:7]
	v_add_u32_e32 v80, 0xffffffb3, v215
	v_cndmask_b32_e32 v102, v102, v203, vcc
	v_cmp_lt_i32_e32 vcc, s84, v80
	v_cmp_gt_i32_e64 s[6:7], s88, v80
	s_or_b64 vcc, vcc, s[6:7]
	v_subrev_u32_e32 v80, 46, v215
	v_cndmask_b32_e32 v86, v86, v203, vcc
	v_cmp_lt_i32_e32 vcc, s84, v80
	v_cmp_gt_i32_e64 s[6:7], s88, v80
	s_or_b64 vcc, vcc, s[6:7]
	v_add_u32_e32 v80, 0xffffffb2, v215
	v_cndmask_b32_e32 v103, v103, v203, vcc
	v_cmp_lt_i32_e32 vcc, s84, v80
	v_cmp_gt_i32_e64 s[6:7], s88, v80
	s_or_b64 vcc, vcc, s[6:7]
	v_subrev_u32_e32 v80, 47, v215
	v_cndmask_b32_e32 v87, v87, v203, vcc
	v_cmp_lt_i32_e32 vcc, s84, v80
	v_cmp_gt_i32_e64 s[6:7], s88, v80
	s_or_b64 vcc, vcc, s[6:7]
	v_add_u32_e32 v80, 0xffffffb1, v215
	v_cndmask_b32_e32 v104, v104, v203, vcc
	v_cmp_lt_i32_e32 vcc, s84, v80
	v_cmp_gt_i32_e64 s[6:7], s88, v80
	s_or_b64 vcc, vcc, s[6:7]
	v_subrev_u32_e32 v80, 48, v215
	v_cndmask_b32_e32 v88, v88, v203, vcc
	v_cmp_lt_i32_e32 vcc, s84, v80
	v_cmp_gt_i32_e64 s[6:7], s88, v80
	s_or_b64 vcc, vcc, s[6:7]
	v_add_u32_e32 v80, 0xffffffb0, v215
	v_cndmask_b32_e32 v105, v105, v203, vcc
	v_cmp_lt_i32_e32 vcc, s84, v80
	v_cmp_gt_i32_e64 s[6:7], s88, v80
	s_or_b64 vcc, vcc, s[6:7]
	v_subrev_u32_e32 v80, 53, v215
	v_cndmask_b32_e32 v89, v89, v203, vcc
	v_cmp_lt_i32_e32 vcc, s84, v80
	v_cmp_gt_i32_e64 s[6:7], s88, v80
	s_or_b64 vcc, vcc, s[6:7]
	v_add_u32_e32 v80, 0xffffffab, v215
	v_cndmask_b32_e32 v106, v106, v203, vcc
	v_cmp_lt_i32_e32 vcc, s84, v80
	v_cmp_gt_i32_e64 s[6:7], s88, v80
	s_or_b64 vcc, vcc, s[6:7]
	v_subrev_u32_e32 v80, 54, v215
	v_cndmask_b32_e32 v90, v90, v203, vcc
	v_cmp_lt_i32_e32 vcc, s84, v80
	v_cmp_gt_i32_e64 s[6:7], s88, v80
	s_or_b64 vcc, vcc, s[6:7]
	v_add_u32_e32 v80, 0xffffffaa, v215
	v_cndmask_b32_e32 v107, v107, v203, vcc
	v_cmp_lt_i32_e32 vcc, s84, v80
	v_cmp_gt_i32_e64 s[6:7], s88, v80
	s_or_b64 vcc, vcc, s[6:7]
	v_subrev_u32_e32 v80, 55, v215
	v_cndmask_b32_e32 v91, v91, v203, vcc
	v_cmp_lt_i32_e32 vcc, s84, v80
	v_cmp_gt_i32_e64 s[6:7], s88, v80
	s_or_b64 vcc, vcc, s[6:7]
	v_add_u32_e32 v80, 0xffffffa9, v215
	v_cndmask_b32_e32 v108, v108, v203, vcc
	v_cmp_lt_i32_e32 vcc, s84, v80
	v_cmp_gt_i32_e64 s[6:7], s88, v80
	s_or_b64 vcc, vcc, s[6:7]
	v_subrev_u32_e32 v80, 56, v215
	v_cndmask_b32_e32 v92, v92, v203, vcc
	v_cmp_lt_i32_e32 vcc, s84, v80
	v_cmp_gt_i32_e64 s[6:7], s88, v80
	s_or_b64 vcc, vcc, s[6:7]
	v_add_u32_e32 v80, 0xffffffa8, v215
	v_cndmask_b32_e32 v109, v109, v203, vcc
	v_cmp_lt_i32_e32 vcc, s84, v80
	v_cmp_gt_i32_e64 s[6:7], s88, v80
	s_or_b64 vcc, vcc, s[6:7]
	v_subrev_u32_e32 v80, 61, v215
	v_cndmask_b32_e32 v93, v93, v203, vcc
	v_cmp_lt_i32_e32 vcc, s84, v80
	v_cmp_gt_i32_e64 s[6:7], s88, v80
	s_or_b64 vcc, vcc, s[6:7]
	v_add_u32_e32 v80, 0xffffffa3, v215
	v_cndmask_b32_e32 v110, v110, v203, vcc
	v_cmp_lt_i32_e32 vcc, s84, v80
	v_cmp_gt_i32_e64 s[6:7], s88, v80
	s_or_b64 vcc, vcc, s[6:7]
	v_subrev_u32_e32 v80, 62, v215
	v_cndmask_b32_e32 v94, v94, v203, vcc
	v_cmp_lt_i32_e32 vcc, s84, v80
	v_cmp_gt_i32_e64 s[6:7], s88, v80
	s_or_b64 vcc, vcc, s[6:7]
	v_add_u32_e32 v80, 0xffffffa2, v215
	v_cndmask_b32_e32 v111, v111, v203, vcc
	v_cmp_lt_i32_e32 vcc, s84, v80
	v_cmp_gt_i32_e64 s[6:7], s88, v80
	s_or_b64 vcc, vcc, s[6:7]
	v_subrev_u32_e32 v80, 63, v215
	v_cndmask_b32_e32 v95, v95, v203, vcc
	v_cmp_lt_i32_e32 vcc, s84, v80
	v_cmp_gt_i32_e64 s[6:7], s88, v80
	s_or_b64 vcc, vcc, s[6:7]
	v_add_u32_e32 v80, 0xffffffa1, v215
	v_cndmask_b32_e32 v112, v112, v203, vcc
	v_cmp_lt_i32_e32 vcc, s84, v80
	v_cmp_gt_i32_e64 s[6:7], s88, v80
	s_or_b64 vcc, vcc, s[6:7]
	v_subrev_u32_e32 v80, 64, v215
	v_cndmask_b32_e32 v96, v96, v203, vcc
	v_cmp_lt_i32_e32 vcc, s84, v80
	v_cmp_gt_i32_e64 s[6:7], s88, v80
	s_or_b64 vcc, vcc, s[6:7]
	v_add_u32_e32 v80, 0xffffffa0, v215
	v_cndmask_b32_e32 v113, v113, v203, vcc
	v_cmp_lt_i32_e32 vcc, s84, v80
	v_cmp_gt_i32_e64 s[6:7], s88, v80
	s_or_b64 vcc, vcc, s[6:7]
	v_cndmask_b32_e32 v97, v97, v203, vcc
.LBB0_598:
	v_lshl_add_u64 v[66:67], v[148:149], 0, s[22:23]
	v_lshl_add_u64 v[70:71], v[150:151], 0, s[22:23]
	v_lshl_add_u64 v[74:75], v[152:153], 0, s[22:23]
	v_lshl_add_u64 v[78:79], v[154:155], 0, s[22:23]
	global_load_dwordx4 v[66:69], v[66:67], off
	s_nop 0
	global_load_dwordx4 v[70:73], v[70:71], off
	s_nop 0
	global_load_dwordx4 v[74:77], v[74:75], off
	s_nop 0
	global_load_dwordx4 v[78:81], v[78:79], off
	ds_read_b64_tr_b16 v[242:243], v214 offset:0
	ds_read_b64_tr_b16 v[244:245], v214 offset:2048
	ds_read_b64_tr_b16 v[246:247], v214 offset:4096
	ds_read_b64_tr_b16 v[248:249], v214 offset:6144
	ds_read_b64_tr_b16 v[196:197], v214 offset:8192
	ds_read_b64_tr_b16 v[198:199], v214 offset:10240
	s_waitcnt lgkmcnt(4)
	v_mfma_f32_32x32x16_bf16 v[50:65], v[228:231], v[242:245], v[50:65]
	ds_read_b64_tr_b16 v[238:239], v214 offset:12288
	ds_read_b64_tr_b16 v[240:241], v214 offset:14336
	s_waitcnt lgkmcnt(4)
	v_mfma_f32_32x32x16_bf16 v[50:65], v[224:227], v[246:249], v[50:65]
	ds_read_b64_tr_b16 v[242:243], v214 offset:512
	ds_read_b64_tr_b16 v[244:245], v214 offset:2560
	s_waitcnt lgkmcnt(4)
	v_mfma_f32_32x32x16_bf16 v[50:65], v[216:219], v[196:199], v[50:65]
	ds_read_b64_tr_b16 v[246:247], v214 offset:4608
	ds_read_b64_tr_b16 v[248:249], v214 offset:6656
	s_waitcnt lgkmcnt(4)
	v_mfma_f32_32x32x16_bf16 v[50:65], v[220:223], v[238:241], v[50:65]
	ds_read_b64_tr_b16 v[196:197], v214 offset:8704
	ds_read_b64_tr_b16 v[198:199], v214 offset:10752
	s_waitcnt lgkmcnt(4)
	v_mfma_f32_32x32x16_bf16 v[34:49], v[228:231], v[242:245], v[34:49]
	ds_read_b64_tr_b16 v[238:239], v214 offset:12800
	ds_read_b64_tr_b16 v[240:241], v214 offset:14848
	s_waitcnt lgkmcnt(4)
	v_mfma_f32_32x32x16_bf16 v[34:49], v[224:227], v[246:249], v[34:49]
	ds_read_b64_tr_b16 v[242:243], v214 offset:1024
	ds_read_b64_tr_b16 v[244:245], v214 offset:3072
	s_waitcnt lgkmcnt(4)
	v_mfma_f32_32x32x16_bf16 v[34:49], v[216:219], v[196:199], v[34:49]
	ds_read_b64_tr_b16 v[246:247], v214 offset:5120
	ds_read_b64_tr_b16 v[248:249], v214 offset:7168
	s_waitcnt lgkmcnt(4)
	v_mfma_f32_32x32x16_bf16 v[34:49], v[220:223], v[238:241], v[34:49]
	ds_read_b64_tr_b16 v[196:197], v214 offset:9216
	ds_read_b64_tr_b16 v[198:199], v214 offset:11264
	s_waitcnt lgkmcnt(4)
	v_mfma_f32_32x32x16_bf16 v[18:33], v[228:231], v[242:245], v[18:33]
	ds_read_b64_tr_b16 v[238:239], v214 offset:13312
	ds_read_b64_tr_b16 v[240:241], v214 offset:15360
	s_waitcnt lgkmcnt(4)
	v_mfma_f32_32x32x16_bf16 v[18:33], v[224:227], v[246:249], v[18:33]
	ds_read_b64_tr_b16 v[242:243], v214 offset:1536
	ds_read_b64_tr_b16 v[244:245], v214 offset:3584
	s_waitcnt lgkmcnt(4)
	v_mfma_f32_32x32x16_bf16 v[18:33], v[216:219], v[196:199], v[18:33]
	ds_read_b64_tr_b16 v[246:247], v214 offset:5632
	ds_read_b64_tr_b16 v[248:249], v214 offset:7680
	s_waitcnt lgkmcnt(4)
	v_mfma_f32_32x32x16_bf16 v[18:33], v[220:223], v[238:241], v[18:33]
	ds_read_b64_tr_b16 v[196:197], v214 offset:9728
	ds_read_b64_tr_b16 v[198:199], v214 offset:11776
	s_waitcnt lgkmcnt(4)
	v_mfma_f32_32x32x16_bf16 v[2:17], v[228:231], v[242:245], v[2:17]
	ds_read_b64_tr_b16 v[238:239], v214 offset:13824
	ds_read_b64_tr_b16 v[240:241], v214 offset:15872
	s_waitcnt lgkmcnt(4)
	v_mfma_f32_32x32x16_bf16 v[2:17], v[224:227], v[246:249], v[2:17]
	s_waitcnt lgkmcnt(2)
	v_mfma_f32_32x32x16_bf16 v[2:17], v[216:219], v[196:199], v[2:17]
	v_max_f32_e32 v216, v99, v99
	v_max_f32_e32 v217, v98, v98
	v_max_f32_e32 v216, v217, v216
	v_max3_f32 v216, v216, v100, v101
	v_max3_f32 v216, v216, v102, v103
	v_max3_f32 v216, v216, v104, v105
	v_max3_f32 v216, v216, v106, v107
	v_max3_f32 v216, v216, v108, v109
	v_max3_f32 v216, v216, v110, v111
	v_max3_f32 v216, v216, v112, v113
	v_max3_f32 v216, v216, v82, v83
	v_max3_f32 v216, v216, v84, v85
	v_max3_f32 v216, v216, v86, v87
	v_max3_f32 v216, v216, v88, v89
	v_max3_f32 v216, v216, v90, v91
	v_max3_f32 v216, v216, v92, v93
	v_max3_f32 v216, v216, v94, v95
	v_max3_f32 v216, v216, v96, v97
	v_mov_b32_e32 v217, v216
	s_nop 1
	v_permlane32_swap_b32_e32 v216, v217
	v_max_f32_e32 v217, v217, v217
	v_max_f32_e32 v216, v216, v216
	v_max_f32_e32 v216, v216, v217
	v_sub_f32_e32 v217, v216, v212
	v_cmp_ge_f32_e32 vcc, s40, v217
	v_max_f32_e32 v217, v212, v212
	v_max_f32_e32 v216, v217, v216
	s_waitcnt lgkmcnt(0)
	v_mfma_f32_32x32x16_bf16 v[2:17], v[220:223], v[238:241], v[2:17]
	v_sub_f32_e32 v217, v212, v216
	v_mul_f32_e32 v217, 0x3e0293ee, v217
	s_barrier
	s_waitcnt vmcnt(3)
	ds_write_b128 v208, v[66:69] offset:16384
	s_waitcnt vmcnt(2)
	ds_write_b128 v209, v[70:73] offset:16384
	s_waitcnt vmcnt(1)
	ds_write_b128 v210, v[74:77] offset:49152
	s_waitcnt vmcnt(0)
	ds_write_b128 v211, v[78:81] offset:49152
	v_exp_f32_e32 v66, v217
	s_cmp_eq_u64 vcc, exec
	s_cselect_b64 s[6:7], -1, 0
	v_cndmask_b32_e64 v234, v66, 1.0, s[6:7]
	v_cmp_gt_f32_e32 vcc, 1.0, v234
	s_cbranch_vccz .LBB0_602
	s_and_saveexec_b64 s[8:9], s[4:5]
	ds_write_b32 v183, v234 offset:128
	s_or_b64 exec, exec, s[8:9]
	s_waitcnt lgkmcnt(0)
	v_add_u32_e32 v78, v181, v146
	ds_read_b128 v[66:69], v78 offset:224
	ds_read_b128 v[70:73], v78 offset:192
	ds_read_b128 v[74:77], v78 offset:128
	ds_read_b128 v[78:81], v78 offset:160
	s_waitcnt lgkmcnt(3)
	v_pk_mul_f32 v[64:65], v[64:65], v[68:69]
	v_pk_mul_f32 v[62:63], v[62:63], v[66:67]
	s_waitcnt lgkmcnt(2)
	v_pk_mul_f32 v[60:61], v[60:61], v[72:73]
	v_pk_mul_f32 v[58:59], v[58:59], v[70:71]
	s_waitcnt lgkmcnt(0)
	v_pk_mul_f32 v[56:57], v[56:57], v[80:81]
	v_pk_mul_f32 v[54:55], v[54:55], v[78:79]
	v_pk_mul_f32 v[52:53], v[52:53], v[76:77]
	v_pk_mul_f32 v[50:51], v[50:51], v[74:75]
	v_pk_mul_f32 v[48:49], v[48:49], v[68:69]
	v_pk_mul_f32 v[46:47], v[46:47], v[66:67]
	v_pk_mul_f32 v[44:45], v[44:45], v[72:73]
	v_pk_mul_f32 v[42:43], v[42:43], v[70:71]
	v_pk_mul_f32 v[40:41], v[40:41], v[80:81]
	v_pk_mul_f32 v[38:39], v[38:39], v[78:79]
	v_pk_mul_f32 v[36:37], v[36:37], v[76:77]
	v_pk_mul_f32 v[34:35], v[34:35], v[74:75]
	v_pk_mul_f32 v[32:33], v[32:33], v[68:69]
	v_pk_mul_f32 v[30:31], v[30:31], v[66:67]
	v_pk_mul_f32 v[28:29], v[28:29], v[72:73]
	v_pk_mul_f32 v[26:27], v[26:27], v[70:71]
	v_pk_mul_f32 v[24:25], v[24:25], v[80:81]
	v_pk_mul_f32 v[22:23], v[22:23], v[78:79]
	v_pk_mul_f32 v[20:21], v[20:21], v[76:77]
	v_pk_mul_f32 v[18:19], v[18:19], v[74:75]
	v_pk_mul_f32 v[16:17], v[16:17], v[68:69]
	v_pk_mul_f32 v[14:15], v[14:15], v[66:67]
	v_pk_mul_f32 v[12:13], v[12:13], v[72:73]
	v_pk_mul_f32 v[10:11], v[10:11], v[70:71]
	v_pk_mul_f32 v[8:9], v[8:9], v[80:81]
	v_pk_mul_f32 v[6:7], v[6:7], v[78:79]
	v_pk_mul_f32 v[4:5], v[4:5], v[76:77]
	v_pk_mul_f32 v[2:3], v[2:3], v[74:75]

	.amdhsa_kernel _Z10fwd_kernel4Args
		.amdhsa_group_segment_fixed_size 0
		.amdhsa_private_segment_fixed_size 0
		.amdhsa_kernarg_size 440
		.amdhsa_user_sgpr_count 2
		.amdhsa_user_sgpr_dispatch_ptr 0
		.amdhsa_user_sgpr_queue_ptr 0
		.amdhsa_user_sgpr_kernarg_segment_ptr 1
		.amdhsa_user_sgpr_dispatch_id 0
		.amdhsa_user_sgpr_kernarg_preload_length 0
		.amdhsa_user_sgpr_kernarg_preload_offset 0
		.amdhsa_user_sgpr_private_segment_size 0
		.amdhsa_uses_dynamic_stack 0
		.amdhsa_enable_private_segment 0
		.amdhsa_system_sgpr_workgroup_id_x 1
		.amdhsa_system_sgpr_workgroup_id_y 0
		.amdhsa_system_sgpr_workgroup_id_z 0
		.amdhsa_system_sgpr_workgroup_info 0
		.amdhsa_system_vgpr_workitem_id 0
		.amdhsa_next_free_vgpr 256
		.amdhsa_next_free_sgpr 100
		.amdhsa_accum_offset 256
		.amdhsa_reserve_vcc 1
		.amdhsa_float_round_mode_32 0
		.amdhsa_float_round_mode_16_64 0
		.amdhsa_float_denorm_mode_32 3
		.amdhsa_float_denorm_mode_16_64 3
		.amdhsa_dx10_clamp 1
		.amdhsa_ieee_mode 1
		.amdhsa_fp16_overflow 0
		.amdhsa_tg_split 0
		.amdhsa_exception_fp_ieee_invalid_op 0
		.amdhsa_exception_fp_denorm_src 0
		.amdhsa_exception_fp_ieee_div_zero 0
		.amdhsa_exception_fp_ieee_overflow 0
		.amdhsa_exception_fp_ieee_underflow 0
		.amdhsa_exception_fp_ieee_inexact 0
		.amdhsa_exception_int_div_zero 0
	.end_amdhsa_kernel

amdhsa.kernels:
  - .agpr_count:     0
    .args:
      - .offset:         0
        .size:           184
        .value_kind:     by_value
      - .offset:         184
        .size:           4
        .value_kind:     hidden_block_count_x
      - .offset:         188
        .size:           4
        .value_kind:     hidden_block_count_y
      - .offset:         192
        .size:           4
        .value_kind:     hidden_block_count_z
      - .offset:         196
        .size:           2
        .value_kind:     hidden_group_size_x
      - .offset:         198
        .size:           2
        .value_kind:     hidden_group_size_y
      - .offset:         200
        .size:           2
        .value_kind:     hidden_group_size_z
      - .offset:         202
        .size:           2
        .value_kind:     hidden_remainder_x
      - .offset:         204
        .size:           2
        .value_kind:     hidden_remainder_y
      - .offset:         206
        .size:           2
        .value_kind:     hidden_remainder_z
      - .offset:         224
        .size:           8
        .value_kind:     hidden_global_offset_x
      - .offset:         232
        .size:           8
        .value_kind:     hidden_global_offset_y
      - .offset:         240
        .size:           8
        .value_kind:     hidden_global_offset_z
      - .offset:         248
        .size:           2
        .value_kind:     hidden_grid_dims
      - .offset:         304
        .size:           4
        .value_kind:     hidden_dynamic_lds_size
    .group_segment_fixed_size: 0
    .kernarg_segment_align: 8
    .kernarg_segment_size: 440
    .language:       OpenCL C
    .language_version:
      - 2
      - 0
    .max_flat_workgroup_size: 512
    .name:           _Z10fwd_kernel4Args
    .private_segment_fixed_size: 0
    .sgpr_count:     106
    .sgpr_spill_count: 24
    .symbol:         _Z10fwd_kernel4Args.kd
    .uniform_work_group_size: 1
    .uses_dynamic_stack: false
    .vgpr_count:     256
    .vgpr_spill_count: 0
    .wavefront_size: 64
